# phase +3 epilogues (gate*acc and T1+gate*acc): 16 serialized load-wait-store steps replaced by 6/12 load sets in rotation with counted vmcnt; stacked on v15
# speedup vs baseline: 1.0161x; 1.0006x over previous
; __device__ __forceinline__ float bflo(unsigned w) { return __uint_as_float(w << 16); }
;     __device__ __forceinline__ void op8(const size_t o, const f32x4 a0, const f32x4 a1) const {
;         const float a[8] = {a0[0], a0[1], a0[2], a0[3], a1[0], a1[1], a1[2], a1[3]};
;         u32x4 g = (u32x4){0u, 0u, 0u, 0u}, x = (u32x4){0u, 0u, 0u, 0u}, t = (u32x4){0u, 0u, 0u, 0u};
;         if (MODE == 0 || MODE == 1) g = *(const u32x4*)(G + o);
;         if (MODE == 1 || MODE == 4) t = *(const u32x4*)((const bf16*)T1 + o);
;         if (MODE == 2 || MODE == 4) x = *(const u32x4*)(X + o);
;         const unsigned gw[4] = {g.x, g.y, g.z, g.w}, xw[4] = {x.x, x.y, x.z, x.w}, tw[4] = {t.x, t.y, t.z, t.w};
;         unsigned w[4];
; #pragma unroll
;         for (int q = 0; q < 4; ++q) { float lo = 0.f, hi = 0.f;
;             if (MODE == 0) { lo = bflo(gw[q]) * a[2 * q]; hi = bfhi(gw[q]) * a[2 * q + 1]; }
;             if (MODE == 1) { lo = bflo(tw[q]) + bflo(gw[q]) * a[2 * q]; hi = bfhi(tw[q]) + bfhi(gw[q]) * a[2 * q + 1]; }
;             if (MODE == 2) { lo = bflo(xw[q]) * DN_ALPHA + a[2 * q]; hi = bfhi(xw[q]) * DN_ALPHA + a[2 * q + 1]; }
;             if (MODE == 3) { lo = a[2 * q]; hi = a[2 * q + 1]; }
;             if (MODE == 4) { lo = bflo(xw[q]) * DN_ALPHA + sigmoid_fast(a[2 * q]) * bflo(tw[q]); hi = bfhi(xw[q]) * DN_ALPHA + sigmoid_fast(a[2 * q + 1]) * bfhi(tw[q]); }
;             w[q] = pk2(lo, hi); }
;         const u32x4 ov = (u32x4){w[0], w[1], w[2], w[3]};
;         if (MODE == 0 || MODE == 3) *(u32x4*)((bf16*)T1 + o) = ov;
;         if (MODE == 1) *(u32x4*)(U + o) = ov;
;         if (MODE == 2) *(u32x4*)(X + o) = ov;
;         if (MODE == 4) *(u32x4*)(Xo + o) = ov;
;     }
;     __device__ __forceinline__ void operator()(const f32x4 (&acc)[2][2][4][2], const Unit& u, int wr, int wc, int fr, int fq) const {
;         const int col0 = u.pn * 256 + wc * 32 + 8 * fq;
; #pragma unroll
;         for (int ai = 0; ai < 2; ++ai)
; #pragma unroll
;             for (int m = 0; m < 4; ++m) {
;                 const size_t off = ((size_t)u.pm * 256 + ai * 128 + wr * 64 + m * 16 + fr) * 1024 + col0;
; #pragma unroll
;                 for (int bj = 0; bj < 2; ++bj) op8(off + bj * 128, acc[ai][bj][m][0], acc[ai][bj][m][1]);
;                 asm volatile("" ::: "memory");
;             }
;     }
.LBB0_1003:
	s_ashr_i32 s11, s10, 31
	s_lshl_b64 s[10:11], s[10:11], 18
	v_lshl_or_b32 v132, s69, 8, v172
	v_ashrrev_i32_e32 v133, 31, v132
	v_lshl_add_u64 v[134:135], s[10:11], 0, v[142:143]
	v_lshl_add_u64 v[132:133], v[134:135], 0, v[132:133]
	v_lshlrev_b64 v[150:151], 1, v[132:133]
	s_mov_b64 s[10:11], 0x8100
	v_lshl_add_u64 v[160:161], v[150:151], 0, s[10:11]
	s_mov_b64 s[10:11], 0x10100
	v_lshl_add_u64 v[158:159], v[150:151], 0, s[10:11]
	s_mov_b64 s[10:11], 0x18100
	v_lshl_add_u64 v[156:157], v[150:151], 0, s[10:11]
	s_mov_b64 s[10:11], 0x40100
	v_lshl_add_u64 v[154:155], v[150:151], 0, s[10:11]
	s_mov_b64 s[10:11], 0x48100
	s_cmp_lg_u32 s70, 0
	v_lshl_add_u64 v[148:149], s[0:1], 0, v[150:151]
	v_or_b32_e32 v162, 0x100, v150
	v_lshl_add_u64 v[152:153], v[150:151], 0, s[10:11]
	s_cbranch_scc0 .LBB0_1009
	v_lshl_add_u64 v[166:167], s[2:3], 0, v[150:151]
	v_lshl_add_u64 v[164:165], s[14:15], 0, v[150:151]
	global_load_dwordx4 v[174:177], v[166:167], off
	global_load_dwordx4 v[178:181], v[148:149], off
	global_load_dwordx4 v[182:185], v[166:167], off offset:256
	global_load_dwordx4 v[186:189], v[148:149], off offset:256
	s_mov_b64 s[10:11], 0x8000
	v_lshl_add_u64 v[238:239], v[166:167], 0, s[10:11]
	global_load_dwordx4 v[190:193], v[238:239], off
	s_mov_b64 s[10:11], 0x8000
	v_lshl_add_u64 v[240:241], v[148:149], 0, s[10:11]
	global_load_dwordx4 v[194:197], v[240:241], off
	s_mov_b64 s[10:11], 0x8000
	v_lshl_add_u64 v[238:239], v[166:167], 0, s[10:11]
	global_load_dwordx4 v[202:205], v[238:239], off offset:256
	s_mov_b64 s[10:11], 0x8000
	v_lshl_add_u64 v[240:241], v[148:149], 0, s[10:11]
	global_load_dwordx4 v[206:209], v[240:241], off offset:256
	s_mov_b64 s[10:11], 0x10000
	v_lshl_add_u64 v[238:239], v[166:167], 0, s[10:11]
	global_load_dwordx4 v[210:213], v[238:239], off
	s_mov_b64 s[10:11], 0x10000
	v_lshl_add_u64 v[240:241], v[148:149], 0, s[10:11]
	global_load_dwordx4 v[214:217], v[240:241], off
	s_mov_b64 s[10:11], 0x10000
	v_lshl_add_u64 v[238:239], v[166:167], 0, s[10:11]
	global_load_dwordx4 v[218:221], v[238:239], off offset:256
	s_mov_b64 s[10:11], 0x10000
	v_lshl_add_u64 v[240:241], v[148:149], 0, s[10:11]
	global_load_dwordx4 v[222:225], v[240:241], off offset:256
	s_waitcnt vmcnt(10)
	v_lshlrev_b32_e32 v132, 16, v178
	v_lshlrev_b32_e32 v227, 16, v174
	v_and_b32_e32 v178, 0xffff0000, v178
	v_and_b32_e32 v174, 0xffff0000, v174
	v_lshlrev_b32_e32 v133, 16, v179
	v_lshlrev_b32_e32 v228, 16, v175
	v_and_b32_e32 v179, 0xffff0000, v179
	v_and_b32_e32 v175, 0xffff0000, v175
	v_lshlrev_b32_e32 v134, 16, v180
	v_lshlrev_b32_e32 v229, 16, v176
	v_and_b32_e32 v180, 0xffff0000, v180
	v_and_b32_e32 v176, 0xffff0000, v176
	v_lshlrev_b32_e32 v135, 16, v181
	v_lshlrev_b32_e32 v230, 16, v177
	v_and_b32_e32 v181, 0xffff0000, v181
	v_and_b32_e32 v177, 0xffff0000, v177
	v_fmac_f32_e32 v132, v128, v227
	v_fmac_f32_e32 v178, v129, v174
	v_fmac_f32_e32 v133, v130, v228
	v_fmac_f32_e32 v179, v131, v175
	v_fmac_f32_e32 v134, v124, v229
	v_fmac_f32_e32 v180, v125, v176
	v_fmac_f32_e32 v135, v126, v230
	v_fmac_f32_e32 v181, v127, v177
	v_cvt_pk_bf16_f32 v174, v132, v178
	v_cvt_pk_bf16_f32 v175, v133, v179
	v_cvt_pk_bf16_f32 v176, v134, v180
	v_cvt_pk_bf16_f32 v177, v135, v181
	global_store_dwordx4 v[164:165], v[174:177], off
	s_mov_b64 s[10:11], 0x18000
	v_lshl_add_u64 v[238:239], v[166:167], 0, s[10:11]
	global_load_dwordx4 v[174:177], v[238:239], off
	s_mov_b64 s[10:11], 0x18000
	v_lshl_add_u64 v[240:241], v[148:149], 0, s[10:11]
	global_load_dwordx4 v[178:181], v[240:241], off
	s_waitcnt vmcnt(11)
	v_lshlrev_b32_e32 v132, 16, v186
	v_lshlrev_b32_e32 v227, 16, v182
	v_and_b32_e32 v186, 0xffff0000, v186
	v_and_b32_e32 v182, 0xffff0000, v182
	v_lshlrev_b32_e32 v133, 16, v187
	v_lshlrev_b32_e32 v228, 16, v183
	v_and_b32_e32 v187, 0xffff0000, v187
	v_and_b32_e32 v183, 0xffff0000, v183
	v_lshlrev_b32_e32 v134, 16, v188
	v_lshlrev_b32_e32 v229, 16, v184
	v_and_b32_e32 v188, 0xffff0000, v188
	v_and_b32_e32 v184, 0xffff0000, v184
	v_lshlrev_b32_e32 v135, 16, v189
	v_lshlrev_b32_e32 v230, 16, v185
	v_and_b32_e32 v189, 0xffff0000, v189
	v_and_b32_e32 v185, 0xffff0000, v185
	v_fmac_f32_e32 v132, v120, v227
	v_fmac_f32_e32 v186, v121, v182
	v_fmac_f32_e32 v133, v122, v228
	v_fmac_f32_e32 v187, v123, v183
	v_fmac_f32_e32 v134, v116, v229
	v_fmac_f32_e32 v188, v117, v184
	v_fmac_f32_e32 v135, v118, v230
	v_fmac_f32_e32 v189, v119, v185
	v_cvt_pk_bf16_f32 v182, v132, v186
	v_cvt_pk_bf16_f32 v183, v133, v187
	v_cvt_pk_bf16_f32 v184, v134, v188
	v_cvt_pk_bf16_f32 v185, v135, v189
	global_store_dwordx4 v[164:165], v[182:185], off offset:256
	s_mov_b64 s[10:11], 0x18000
	v_lshl_add_u64 v[238:239], v[166:167], 0, s[10:11]
	global_load_dwordx4 v[182:185], v[238:239], off offset:256
	s_mov_b64 s[10:11], 0x18000
	v_lshl_add_u64 v[240:241], v[148:149], 0, s[10:11]
	global_load_dwordx4 v[186:189], v[240:241], off offset:256
	s_waitcnt vmcnt(12)
	v_lshlrev_b32_e32 v132, 16, v194
	v_lshlrev_b32_e32 v227, 16, v190
	v_and_b32_e32 v194, 0xffff0000, v194
	v_and_b32_e32 v190, 0xffff0000, v190
	v_lshlrev_b32_e32 v133, 16, v195
	v_lshlrev_b32_e32 v228, 16, v191
	v_and_b32_e32 v195, 0xffff0000, v195
	v_and_b32_e32 v191, 0xffff0000, v191
	v_lshlrev_b32_e32 v134, 16, v196
	v_lshlrev_b32_e32 v229, 16, v192
	v_and_b32_e32 v196, 0xffff0000, v196
	v_and_b32_e32 v192, 0xffff0000, v192
	v_lshlrev_b32_e32 v135, 16, v197
	v_lshlrev_b32_e32 v230, 16, v193
	v_and_b32_e32 v197, 0xffff0000, v197
	v_and_b32_e32 v193, 0xffff0000, v193
	v_fmac_f32_e32 v132, v112, v227
	v_fmac_f32_e32 v194, v113, v190
	v_fmac_f32_e32 v133, v114, v228
	v_fmac_f32_e32 v195, v115, v191
	v_fmac_f32_e32 v134, v108, v229
	v_fmac_f32_e32 v196, v109, v192
	v_fmac_f32_e32 v135, v110, v230
	v_fmac_f32_e32 v197, v111, v193
	v_cvt_pk_bf16_f32 v190, v132, v194
	v_cvt_pk_bf16_f32 v191, v133, v195
	v_cvt_pk_bf16_f32 v192, v134, v196
	v_cvt_pk_bf16_f32 v193, v135, v197
	s_mov_b64 s[10:11], 0x8000
	v_lshl_add_u64 v[242:243], v[164:165], 0, s[10:11]
	global_store_dwordx4 v[242:243], v[190:193], off
	s_mov_b64 s[10:11], 0x40000
	v_lshl_add_u64 v[238:239], v[166:167], 0, s[10:11]
	global_load_dwordx4 v[190:193], v[238:239], off
	s_mov_b64 s[10:11], 0x40000
	v_lshl_add_u64 v[240:241], v[148:149], 0, s[10:11]
	global_load_dwordx4 v[194:197], v[240:241], off
	s_waitcnt vmcnt(13)
; __device__ __forceinline__ float bflo(unsigned w) { return __uint_as_float(w << 16); }
;     __device__ __forceinline__ void op8(const size_t o, const f32x4 a0, const f32x4 a1) const {
;         const float a[8] = {a0[0], a0[1], a0[2], a0[3], a1[0], a1[1], a1[2], a1[3]};
;         u32x4 g = (u32x4){0u, 0u, 0u, 0u}, x = (u32x4){0u, 0u, 0u, 0u}, t = (u32x4){0u, 0u, 0u, 0u};
;         if (MODE == 0 || MODE == 1) g = *(const u32x4*)(G + o);
;         if (MODE == 1 || MODE == 4) t = *(const u32x4*)((const bf16*)T1 + o);
;         if (MODE == 2 || MODE == 4) x = *(const u32x4*)(X + o);
;         const unsigned gw[4] = {g.x, g.y, g.z, g.w}, xw[4] = {x.x, x.y, x.z, x.w}, tw[4] = {t.x, t.y, t.z, t.w};
;         unsigned w[4];
; #pragma unroll
;         for (int q = 0; q < 4; ++q) { float lo = 0.f, hi = 0.f;
;             if (MODE == 0) { lo = bflo(gw[q]) * a[2 * q]; hi = bfhi(gw[q]) * a[2 * q + 1]; }
;             if (MODE == 1) { lo = bflo(tw[q]) + bflo(gw[q]) * a[2 * q]; hi = bfhi(tw[q]) + bfhi(gw[q]) * a[2 * q + 1]; }
;             if (MODE == 2) { lo = bflo(xw[q]) * DN_ALPHA + a[2 * q]; hi = bfhi(xw[q]) * DN_ALPHA + a[2 * q + 1]; }
;             if (MODE == 3) { lo = a[2 * q]; hi = a[2 * q + 1]; }
;             if (MODE == 4) { lo = bflo(xw[q]) * DN_ALPHA + sigmoid_fast(a[2 * q]) * bflo(tw[q]); hi = bfhi(xw[q]) * DN_ALPHA + sigmoid_fast(a[2 * q + 1]) * bfhi(tw[q]); }
;             w[q] = pk2(lo, hi); }
;         const u32x4 ov = (u32x4){w[0], w[1], w[2], w[3]};
;         if (MODE == 0 || MODE == 3) *(u32x4*)((bf16*)T1 + o) = ov;
;         if (MODE == 1) *(u32x4*)(U + o) = ov;
;         if (MODE == 2) *(u32x4*)(X + o) = ov;
;         if (MODE == 4) *(u32x4*)(Xo + o) = ov;
;     }
;     __device__ __forceinline__ void operator()(const f32x4 (&acc)[2][2][4][2], const Unit& u, int wr, int wc, int fr, int fq) const {
;         const int col0 = u.pn * 256 + wc * 32 + 8 * fq;
; #pragma unroll
;         for (int ai = 0; ai < 2; ++ai)
; #pragma unroll
;             for (int m = 0; m < 4; ++m) {
;                 const size_t off = ((size_t)u.pm * 256 + ai * 128 + wr * 64 + m * 16 + fr) * 1024 + col0;
; #pragma unroll
;                 for (int bj = 0; bj < 2; ++bj) op8(off + bj * 128, acc[ai][bj][m][0], acc[ai][bj][m][1]);
;                 asm volatile("" ::: "memory");
;             }
;     }
	v_lshlrev_b32_e32 v132, 16, v206
	v_lshlrev_b32_e32 v227, 16, v202
	v_and_b32_e32 v206, 0xffff0000, v206
	v_and_b32_e32 v202, 0xffff0000, v202
	v_lshlrev_b32_e32 v133, 16, v207
	v_lshlrev_b32_e32 v228, 16, v203
	v_and_b32_e32 v207, 0xffff0000, v207
	v_and_b32_e32 v203, 0xffff0000, v203
	v_lshlrev_b32_e32 v134, 16, v208
	v_lshlrev_b32_e32 v229, 16, v204
	v_and_b32_e32 v208, 0xffff0000, v208
	v_and_b32_e32 v204, 0xffff0000, v204
	v_lshlrev_b32_e32 v135, 16, v209
	v_lshlrev_b32_e32 v230, 16, v205
	v_and_b32_e32 v209, 0xffff0000, v209
	v_and_b32_e32 v205, 0xffff0000, v205
	v_fmac_f32_e32 v132, v104, v227
	v_fmac_f32_e32 v206, v105, v202
	v_fmac_f32_e32 v133, v106, v228
	v_fmac_f32_e32 v207, v107, v203
	v_fmac_f32_e32 v134, v100, v229
	v_fmac_f32_e32 v208, v101, v204
	v_fmac_f32_e32 v135, v102, v230
	v_fmac_f32_e32 v209, v103, v205
	v_cvt_pk_bf16_f32 v202, v132, v206
	v_cvt_pk_bf16_f32 v203, v133, v207
	v_cvt_pk_bf16_f32 v204, v134, v208
	v_cvt_pk_bf16_f32 v205, v135, v209
	s_mov_b64 s[10:11], 0x8000
	v_lshl_add_u64 v[242:243], v[164:165], 0, s[10:11]
	global_store_dwordx4 v[242:243], v[202:205], off offset:256
	s_mov_b64 s[10:11], 0x40000
	v_lshl_add_u64 v[238:239], v[166:167], 0, s[10:11]
	global_load_dwordx4 v[202:205], v[238:239], off offset:256
	s_mov_b64 s[10:11], 0x40000
	v_lshl_add_u64 v[240:241], v[148:149], 0, s[10:11]
	global_load_dwordx4 v[206:209], v[240:241], off offset:256
	s_waitcnt vmcnt(14)
	v_lshlrev_b32_e32 v132, 16, v214
	v_lshlrev_b32_e32 v227, 16, v210
	v_and_b32_e32 v214, 0xffff0000, v214
	v_and_b32_e32 v210, 0xffff0000, v210
	v_lshlrev_b32_e32 v133, 16, v215
	v_lshlrev_b32_e32 v228, 16, v211
	v_and_b32_e32 v215, 0xffff0000, v215
	v_and_b32_e32 v211, 0xffff0000, v211
	v_lshlrev_b32_e32 v134, 16, v216
	v_lshlrev_b32_e32 v229, 16, v212
	v_and_b32_e32 v216, 0xffff0000, v216
	v_and_b32_e32 v212, 0xffff0000, v212
	v_lshlrev_b32_e32 v135, 16, v217
	v_lshlrev_b32_e32 v230, 16, v213
	v_and_b32_e32 v217, 0xffff0000, v217
	v_and_b32_e32 v213, 0xffff0000, v213
	v_fmac_f32_e32 v132, v96, v227
	v_fmac_f32_e32 v214, v97, v210
	v_fmac_f32_e32 v133, v98, v228
	v_fmac_f32_e32 v215, v99, v211
	v_fmac_f32_e32 v134, v92, v229
	v_fmac_f32_e32 v216, v93, v212
	v_fmac_f32_e32 v135, v94, v230
	v_fmac_f32_e32 v217, v95, v213
	v_cvt_pk_bf16_f32 v210, v132, v214
	v_cvt_pk_bf16_f32 v211, v133, v215
	v_cvt_pk_bf16_f32 v212, v134, v216
	v_cvt_pk_bf16_f32 v213, v135, v217
	s_mov_b64 s[10:11], 0x10000
	v_lshl_add_u64 v[242:243], v[164:165], 0, s[10:11]
	global_store_dwordx4 v[242:243], v[210:213], off
	s_mov_b64 s[10:11], 0x48000
	v_lshl_add_u64 v[238:239], v[166:167], 0, s[10:11]
	global_load_dwordx4 v[210:213], v[238:239], off
	s_mov_b64 s[10:11], 0x48000
	v_lshl_add_u64 v[240:241], v[148:149], 0, s[10:11]
	global_load_dwordx4 v[214:217], v[240:241], off
	s_waitcnt vmcnt(15)
	v_lshlrev_b32_e32 v132, 16, v222
	v_lshlrev_b32_e32 v227, 16, v218
	v_and_b32_e32 v222, 0xffff0000, v222
	v_and_b32_e32 v218, 0xffff0000, v218
	v_lshlrev_b32_e32 v133, 16, v223
	v_lshlrev_b32_e32 v228, 16, v219
	v_and_b32_e32 v223, 0xffff0000, v223
	v_and_b32_e32 v219, 0xffff0000, v219
	v_lshlrev_b32_e32 v134, 16, v224
	v_lshlrev_b32_e32 v229, 16, v220
	v_and_b32_e32 v224, 0xffff0000, v224
	v_and_b32_e32 v220, 0xffff0000, v220
	v_lshlrev_b32_e32 v135, 16, v225
	v_lshlrev_b32_e32 v230, 16, v221
	v_and_b32_e32 v225, 0xffff0000, v225
	v_and_b32_e32 v221, 0xffff0000, v221
	v_fmac_f32_e32 v132, v88, v227
	v_fmac_f32_e32 v222, v89, v218
	v_fmac_f32_e32 v133, v90, v228
	v_fmac_f32_e32 v223, v91, v219
	v_fmac_f32_e32 v134, v84, v229
	v_fmac_f32_e32 v224, v85, v220
	v_fmac_f32_e32 v135, v86, v230
	v_fmac_f32_e32 v225, v87, v221
	v_cvt_pk_bf16_f32 v218, v132, v222
	v_cvt_pk_bf16_f32 v219, v133, v223
	v_cvt_pk_bf16_f32 v220, v134, v224
	v_cvt_pk_bf16_f32 v221, v135, v225
	s_mov_b64 s[10:11], 0x10000
	v_lshl_add_u64 v[242:243], v[164:165], 0, s[10:11]
	global_store_dwordx4 v[242:243], v[218:221], off offset:256
	s_mov_b64 s[10:11], 0x48000
	v_lshl_add_u64 v[238:239], v[166:167], 0, s[10:11]
	global_load_dwordx4 v[218:221], v[238:239], off offset:256
	s_mov_b64 s[10:11], 0x48000
	v_lshl_add_u64 v[240:241], v[148:149], 0, s[10:11]
	global_load_dwordx4 v[222:225], v[240:241], off offset:256
	s_waitcnt vmcnt(15)
	v_lshlrev_b32_e32 v132, 16, v178
	v_lshlrev_b32_e32 v227, 16, v174
	v_and_b32_e32 v178, 0xffff0000, v178
	v_and_b32_e32 v174, 0xffff0000, v174
	v_lshlrev_b32_e32 v133, 16, v179
	v_lshlrev_b32_e32 v228, 16, v175
	v_and_b32_e32 v179, 0xffff0000, v179
	v_and_b32_e32 v175, 0xffff0000, v175
	v_lshlrev_b32_e32 v134, 16, v180
	v_lshlrev_b32_e32 v229, 16, v176
	v_and_b32_e32 v180, 0xffff0000, v180
	v_and_b32_e32 v176, 0xffff0000, v176
	v_lshlrev_b32_e32 v135, 16, v181
	v_lshlrev_b32_e32 v230, 16, v177
	v_and_b32_e32 v181, 0xffff0000, v181
	v_and_b32_e32 v177, 0xffff0000, v177
	v_fmac_f32_e32 v132, v80, v227
	v_fmac_f32_e32 v178, v81, v174
	v_fmac_f32_e32 v133, v82, v228
	v_fmac_f32_e32 v179, v83, v175
	v_fmac_f32_e32 v134, v76, v229
	v_fmac_f32_e32 v180, v77, v176
	v_fmac_f32_e32 v135, v78, v230
	v_fmac_f32_e32 v181, v79, v177
	v_cvt_pk_bf16_f32 v174, v132, v178
	v_cvt_pk_bf16_f32 v175, v133, v179
	v_cvt_pk_bf16_f32 v176, v134, v180
	v_cvt_pk_bf16_f32 v177, v135, v181
	s_mov_b64 s[10:11], 0x18000
	v_lshl_add_u64 v[242:243], v[164:165], 0, s[10:11]
	global_store_dwordx4 v[242:243], v[174:177], off
	s_mov_b64 s[10:11], 0x50000
	v_lshl_add_u64 v[238:239], v[166:167], 0, s[10:11]
	global_load_dwordx4 v[174:177], v[238:239], off
	s_mov_b64 s[10:11], 0x50000
	v_lshl_add_u64 v[240:241], v[148:149], 0, s[10:11]
	global_load_dwordx4 v[178:181], v[240:241], off
	s_waitcnt vmcnt(15)
; __device__ __forceinline__ float bflo(unsigned w) { return __uint_as_float(w << 16); }
;     __device__ __forceinline__ void op8(const size_t o, const f32x4 a0, const f32x4 a1) const {
;         const float a[8] = {a0[0], a0[1], a0[2], a0[3], a1[0], a1[1], a1[2], a1[3]};
;         u32x4 g = (u32x4){0u, 0u, 0u, 0u}, x = (u32x4){0u, 0u, 0u, 0u}, t = (u32x4){0u, 0u, 0u, 0u};
;         if (MODE == 0 || MODE == 1) g = *(const u32x4*)(G + o);
;         if (MODE == 1 || MODE == 4) t = *(const u32x4*)((const bf16*)T1 + o);
;         if (MODE == 2 || MODE == 4) x = *(const u32x4*)(X + o);
;         const unsigned gw[4] = {g.x, g.y, g.z, g.w}, xw[4] = {x.x, x.y, x.z, x.w}, tw[4] = {t.x, t.y, t.z, t.w};
;         unsigned w[4];
; #pragma unroll
;         for (int q = 0; q < 4; ++q) { float lo = 0.f, hi = 0.f;
;             if (MODE == 0) { lo = bflo(gw[q]) * a[2 * q]; hi = bfhi(gw[q]) * a[2 * q + 1]; }
;             if (MODE == 1) { lo = bflo(tw[q]) + bflo(gw[q]) * a[2 * q]; hi = bfhi(tw[q]) + bfhi(gw[q]) * a[2 * q + 1]; }
;             if (MODE == 2) { lo = bflo(xw[q]) * DN_ALPHA + a[2 * q]; hi = bfhi(xw[q]) * DN_ALPHA + a[2 * q + 1]; }
;             if (MODE == 3) { lo = a[2 * q]; hi = a[2 * q + 1]; }
;             if (MODE == 4) { lo = bflo(xw[q]) * DN_ALPHA + sigmoid_fast(a[2 * q]) * bflo(tw[q]); hi = bfhi(xw[q]) * DN_ALPHA + sigmoid_fast(a[2 * q + 1]) * bfhi(tw[q]); }
;             w[q] = pk2(lo, hi); }
;         const u32x4 ov = (u32x4){w[0], w[1], w[2], w[3]};
;         if (MODE == 0 || MODE == 3) *(u32x4*)((bf16*)T1 + o) = ov;
;         if (MODE == 1) *(u32x4*)(U + o) = ov;
;         if (MODE == 2) *(u32x4*)(X + o) = ov;
;         if (MODE == 4) *(u32x4*)(Xo + o) = ov;
;     }
;     __device__ __forceinline__ void operator()(const f32x4 (&acc)[2][2][4][2], const Unit& u, int wr, int wc, int fr, int fq) const {
;         const int col0 = u.pn * 256 + wc * 32 + 8 * fq;
; #pragma unroll
;         for (int ai = 0; ai < 2; ++ai)
; #pragma unroll
;             for (int m = 0; m < 4; ++m) {
;                 const size_t off = ((size_t)u.pm * 256 + ai * 128 + wr * 64 + m * 16 + fr) * 1024 + col0;
; #pragma unroll
;                 for (int bj = 0; bj < 2; ++bj) op8(off + bj * 128, acc[ai][bj][m][0], acc[ai][bj][m][1]);
;                 asm volatile("" ::: "memory");
;             }
;     }
	v_lshlrev_b32_e32 v132, 16, v186
	v_lshlrev_b32_e32 v227, 16, v182
	v_and_b32_e32 v186, 0xffff0000, v186
	v_and_b32_e32 v182, 0xffff0000, v182
	v_lshlrev_b32_e32 v133, 16, v187
	v_lshlrev_b32_e32 v228, 16, v183
	v_and_b32_e32 v187, 0xffff0000, v187
	v_and_b32_e32 v183, 0xffff0000, v183
	v_lshlrev_b32_e32 v134, 16, v188
	v_lshlrev_b32_e32 v229, 16, v184
	v_and_b32_e32 v188, 0xffff0000, v188
	v_and_b32_e32 v184, 0xffff0000, v184
	v_lshlrev_b32_e32 v135, 16, v189
	v_lshlrev_b32_e32 v230, 16, v185
	v_and_b32_e32 v189, 0xffff0000, v189
	v_and_b32_e32 v185, 0xffff0000, v185
	v_fmac_f32_e32 v132, v72, v227
	v_fmac_f32_e32 v186, v73, v182
	v_fmac_f32_e32 v133, v74, v228
	v_fmac_f32_e32 v187, v75, v183
	v_fmac_f32_e32 v134, v68, v229
	v_fmac_f32_e32 v188, v69, v184
	v_fmac_f32_e32 v135, v70, v230
	v_fmac_f32_e32 v189, v71, v185
	v_cvt_pk_bf16_f32 v182, v132, v186
	v_cvt_pk_bf16_f32 v183, v133, v187
	v_cvt_pk_bf16_f32 v184, v134, v188
	v_cvt_pk_bf16_f32 v185, v135, v189
	s_mov_b64 s[10:11], 0x18000
	v_lshl_add_u64 v[242:243], v[164:165], 0, s[10:11]
	global_store_dwordx4 v[242:243], v[182:185], off offset:256
	s_mov_b64 s[10:11], 0x50000
	v_lshl_add_u64 v[238:239], v[166:167], 0, s[10:11]
	global_load_dwordx4 v[182:185], v[238:239], off offset:256
	s_mov_b64 s[10:11], 0x50000
	v_lshl_add_u64 v[240:241], v[148:149], 0, s[10:11]
	global_load_dwordx4 v[186:189], v[240:241], off offset:256
	s_waitcnt vmcnt(15)
	v_lshlrev_b32_e32 v132, 16, v194
	v_lshlrev_b32_e32 v227, 16, v190
	v_and_b32_e32 v194, 0xffff0000, v194
	v_and_b32_e32 v190, 0xffff0000, v190
	v_lshlrev_b32_e32 v133, 16, v195
	v_lshlrev_b32_e32 v228, 16, v191
	v_and_b32_e32 v195, 0xffff0000, v195
	v_and_b32_e32 v191, 0xffff0000, v191
	v_lshlrev_b32_e32 v134, 16, v196
	v_lshlrev_b32_e32 v229, 16, v192
	v_and_b32_e32 v196, 0xffff0000, v196
	v_and_b32_e32 v192, 0xffff0000, v192
	v_lshlrev_b32_e32 v135, 16, v197
	v_lshlrev_b32_e32 v230, 16, v193
	v_and_b32_e32 v197, 0xffff0000, v197
	v_and_b32_e32 v193, 0xffff0000, v193
	v_fmac_f32_e32 v132, v64, v227
	v_fmac_f32_e32 v194, v65, v190
	v_fmac_f32_e32 v133, v66, v228
	v_fmac_f32_e32 v195, v67, v191
	v_fmac_f32_e32 v134, v60, v229
	v_fmac_f32_e32 v196, v61, v192
	v_fmac_f32_e32 v135, v62, v230
	v_fmac_f32_e32 v197, v63, v193
	v_cvt_pk_bf16_f32 v190, v132, v194
	v_cvt_pk_bf16_f32 v191, v133, v195
	v_cvt_pk_bf16_f32 v192, v134, v196
	v_cvt_pk_bf16_f32 v193, v135, v197
	s_mov_b64 s[10:11], 0x40000
	v_lshl_add_u64 v[242:243], v[164:165], 0, s[10:11]
	global_store_dwordx4 v[242:243], v[190:193], off
	s_mov_b64 s[10:11], 0x58000
	v_lshl_add_u64 v[238:239], v[166:167], 0, s[10:11]
	global_load_dwordx4 v[190:193], v[238:239], off
	s_mov_b64 s[10:11], 0x58000
	v_lshl_add_u64 v[240:241], v[148:149], 0, s[10:11]
	global_load_dwordx4 v[194:197], v[240:241], off
	s_waitcnt vmcnt(15)
	v_lshlrev_b32_e32 v132, 16, v206
	v_lshlrev_b32_e32 v227, 16, v202
	v_and_b32_e32 v206, 0xffff0000, v206
	v_and_b32_e32 v202, 0xffff0000, v202
	v_lshlrev_b32_e32 v133, 16, v207
	v_lshlrev_b32_e32 v228, 16, v203
	v_and_b32_e32 v207, 0xffff0000, v207
	v_and_b32_e32 v203, 0xffff0000, v203
	v_lshlrev_b32_e32 v134, 16, v208
	v_lshlrev_b32_e32 v229, 16, v204
	v_and_b32_e32 v208, 0xffff0000, v208
	v_and_b32_e32 v204, 0xffff0000, v204
	v_lshlrev_b32_e32 v135, 16, v209
	v_lshlrev_b32_e32 v230, 16, v205
	v_and_b32_e32 v209, 0xffff0000, v209
	v_and_b32_e32 v205, 0xffff0000, v205
	v_fmac_f32_e32 v132, v56, v227
	v_fmac_f32_e32 v206, v57, v202
	v_fmac_f32_e32 v133, v58, v228
	v_fmac_f32_e32 v207, v59, v203
	v_fmac_f32_e32 v134, v52, v229
	v_fmac_f32_e32 v208, v53, v204
	v_fmac_f32_e32 v135, v54, v230
	v_fmac_f32_e32 v209, v55, v205
	v_cvt_pk_bf16_f32 v202, v132, v206
	v_cvt_pk_bf16_f32 v203, v133, v207
	v_cvt_pk_bf16_f32 v204, v134, v208
	v_cvt_pk_bf16_f32 v205, v135, v209
	s_mov_b64 s[10:11], 0x40000
	v_lshl_add_u64 v[242:243], v[164:165], 0, s[10:11]
	global_store_dwordx4 v[242:243], v[202:205], off offset:256
	s_mov_b64 s[10:11], 0x58000
	v_lshl_add_u64 v[238:239], v[166:167], 0, s[10:11]
	global_load_dwordx4 v[202:205], v[238:239], off offset:256
	s_mov_b64 s[10:11], 0x58000
	v_lshl_add_u64 v[240:241], v[148:149], 0, s[10:11]
	global_load_dwordx4 v[206:209], v[240:241], off offset:256
	s_waitcnt vmcnt(15)
	v_lshlrev_b32_e32 v132, 16, v214
	v_lshlrev_b32_e32 v227, 16, v210
	v_and_b32_e32 v214, 0xffff0000, v214
	v_and_b32_e32 v210, 0xffff0000, v210
	v_lshlrev_b32_e32 v133, 16, v215
	v_lshlrev_b32_e32 v228, 16, v211
	v_and_b32_e32 v215, 0xffff0000, v215
	v_and_b32_e32 v211, 0xffff0000, v211
	v_lshlrev_b32_e32 v134, 16, v216
	v_lshlrev_b32_e32 v229, 16, v212
	v_and_b32_e32 v216, 0xffff0000, v216
	v_and_b32_e32 v212, 0xffff0000, v212
	v_lshlrev_b32_e32 v135, 16, v217
	v_lshlrev_b32_e32 v230, 16, v213
	v_and_b32_e32 v217, 0xffff0000, v217
	v_and_b32_e32 v213, 0xffff0000, v213
	v_fmac_f32_e32 v132, v48, v227
	v_fmac_f32_e32 v214, v49, v210
	v_fmac_f32_e32 v133, v50, v228
	v_fmac_f32_e32 v215, v51, v211
	v_fmac_f32_e32 v134, v44, v229
	v_fmac_f32_e32 v216, v45, v212
	v_fmac_f32_e32 v135, v46, v230
	v_fmac_f32_e32 v217, v47, v213
	v_cvt_pk_bf16_f32 v210, v132, v214
	v_cvt_pk_bf16_f32 v211, v133, v215
	v_cvt_pk_bf16_f32 v212, v134, v216
	v_cvt_pk_bf16_f32 v213, v135, v217
	s_mov_b64 s[10:11], 0x48000
	v_lshl_add_u64 v[242:243], v[164:165], 0, s[10:11]
	global_store_dwordx4 v[242:243], v[210:213], off
	s_waitcnt vmcnt(13)
; __device__ __forceinline__ float bflo(unsigned w) { return __uint_as_float(w << 16); }
;     __device__ __forceinline__ void op8(const size_t o, const f32x4 a0, const f32x4 a1) const {
;         const float a[8] = {a0[0], a0[1], a0[2], a0[3], a1[0], a1[1], a1[2], a1[3]};
;         u32x4 g = (u32x4){0u, 0u, 0u, 0u}, x = (u32x4){0u, 0u, 0u, 0u}, t = (u32x4){0u, 0u, 0u, 0u};
;         if (MODE == 0 || MODE == 1) g = *(const u32x4*)(G + o);
;         if (MODE == 1 || MODE == 4) t = *(const u32x4*)((const bf16*)T1 + o);
;         if (MODE == 2 || MODE == 4) x = *(const u32x4*)(X + o);
;         const unsigned gw[4] = {g.x, g.y, g.z, g.w}, xw[4] = {x.x, x.y, x.z, x.w}, tw[4] = {t.x, t.y, t.z, t.w};
;         unsigned w[4];
; #pragma unroll
;         for (int q = 0; q < 4; ++q) { float lo = 0.f, hi = 0.f;
;             if (MODE == 0) { lo = bflo(gw[q]) * a[2 * q]; hi = bfhi(gw[q]) * a[2 * q + 1]; }
;             if (MODE == 1) { lo = bflo(tw[q]) + bflo(gw[q]) * a[2 * q]; hi = bfhi(tw[q]) + bfhi(gw[q]) * a[2 * q + 1]; }
;             if (MODE == 2) { lo = bflo(xw[q]) * DN_ALPHA + a[2 * q]; hi = bfhi(xw[q]) * DN_ALPHA + a[2 * q + 1]; }
;             if (MODE == 3) { lo = a[2 * q]; hi = a[2 * q + 1]; }
;             if (MODE == 4) { lo = bflo(xw[q]) * DN_ALPHA + sigmoid_fast(a[2 * q]) * bflo(tw[q]); hi = bfhi(xw[q]) * DN_ALPHA + sigmoid_fast(a[2 * q + 1]) * bfhi(tw[q]); }
;             w[q] = pk2(lo, hi); }
;         const u32x4 ov = (u32x4){w[0], w[1], w[2], w[3]};
;         if (MODE == 0 || MODE == 3) *(u32x4*)((bf16*)T1 + o) = ov;
;         if (MODE == 1) *(u32x4*)(U + o) = ov;
;         if (MODE == 2) *(u32x4*)(X + o) = ov;
;         if (MODE == 4) *(u32x4*)(Xo + o) = ov;
;     }
;     __device__ __forceinline__ void operator()(const f32x4 (&acc)[2][2][4][2], const Unit& u, int wr, int wc, int fr, int fq) const {
;         const int col0 = u.pn * 256 + wc * 32 + 8 * fq;
; #pragma unroll
;         for (int ai = 0; ai < 2; ++ai)
; #pragma unroll
;             for (int m = 0; m < 4; ++m) {
;                 const size_t off = ((size_t)u.pm * 256 + ai * 128 + wr * 64 + m * 16 + fr) * 1024 + col0;
; #pragma unroll
;                 for (int bj = 0; bj < 2; ++bj) op8(off + bj * 128, acc[ai][bj][m][0], acc[ai][bj][m][1]);
;                 asm volatile("" ::: "memory");
;             }
;     }
	v_lshlrev_b32_e32 v132, 16, v222
	v_lshlrev_b32_e32 v227, 16, v218
	v_and_b32_e32 v222, 0xffff0000, v222
	v_and_b32_e32 v218, 0xffff0000, v218
	v_lshlrev_b32_e32 v133, 16, v223
	v_lshlrev_b32_e32 v228, 16, v219
	v_and_b32_e32 v223, 0xffff0000, v223
	v_and_b32_e32 v219, 0xffff0000, v219
	v_lshlrev_b32_e32 v134, 16, v224
	v_lshlrev_b32_e32 v229, 16, v220
	v_and_b32_e32 v224, 0xffff0000, v224
	v_and_b32_e32 v220, 0xffff0000, v220
	v_lshlrev_b32_e32 v135, 16, v225
	v_lshlrev_b32_e32 v230, 16, v221
	v_and_b32_e32 v225, 0xffff0000, v225
	v_and_b32_e32 v221, 0xffff0000, v221
	v_fmac_f32_e32 v132, v40, v227
	v_fmac_f32_e32 v222, v41, v218
	v_fmac_f32_e32 v133, v42, v228
	v_fmac_f32_e32 v223, v43, v219
	v_fmac_f32_e32 v134, v36, v229
	v_fmac_f32_e32 v224, v37, v220
	v_fmac_f32_e32 v135, v38, v230
	v_fmac_f32_e32 v225, v39, v221
	v_cvt_pk_bf16_f32 v218, v132, v222
	v_cvt_pk_bf16_f32 v219, v133, v223
	v_cvt_pk_bf16_f32 v220, v134, v224
	v_cvt_pk_bf16_f32 v221, v135, v225
	s_mov_b64 s[10:11], 0x48000
	v_lshl_add_u64 v[242:243], v[164:165], 0, s[10:11]
	global_store_dwordx4 v[242:243], v[218:221], off offset:256
	s_waitcnt vmcnt(11)
	v_lshlrev_b32_e32 v132, 16, v178
	v_lshlrev_b32_e32 v227, 16, v174
	v_and_b32_e32 v178, 0xffff0000, v178
	v_and_b32_e32 v174, 0xffff0000, v174
	v_lshlrev_b32_e32 v133, 16, v179
	v_lshlrev_b32_e32 v228, 16, v175
	v_and_b32_e32 v179, 0xffff0000, v179
	v_and_b32_e32 v175, 0xffff0000, v175
	v_lshlrev_b32_e32 v134, 16, v180
	v_lshlrev_b32_e32 v229, 16, v176
	v_and_b32_e32 v180, 0xffff0000, v180
	v_and_b32_e32 v176, 0xffff0000, v176
	v_lshlrev_b32_e32 v135, 16, v181
	v_lshlrev_b32_e32 v230, 16, v177
	v_and_b32_e32 v181, 0xffff0000, v181
	v_and_b32_e32 v177, 0xffff0000, v177
	v_fmac_f32_e32 v132, v32, v227
	v_fmac_f32_e32 v178, v33, v174
	v_fmac_f32_e32 v133, v34, v228
	v_fmac_f32_e32 v179, v35, v175
	v_fmac_f32_e32 v134, v28, v229
	v_fmac_f32_e32 v180, v29, v176
	v_fmac_f32_e32 v135, v30, v230
	v_fmac_f32_e32 v181, v31, v177
	v_cvt_pk_bf16_f32 v174, v132, v178
	v_cvt_pk_bf16_f32 v175, v133, v179
	v_cvt_pk_bf16_f32 v176, v134, v180
	v_cvt_pk_bf16_f32 v177, v135, v181
	s_mov_b64 s[10:11], 0x50000
	v_lshl_add_u64 v[242:243], v[164:165], 0, s[10:11]
	global_store_dwordx4 v[242:243], v[174:177], off
	s_waitcnt vmcnt(9)
	v_lshlrev_b32_e32 v132, 16, v186
	v_lshlrev_b32_e32 v227, 16, v182
	v_and_b32_e32 v186, 0xffff0000, v186
	v_and_b32_e32 v182, 0xffff0000, v182
	v_lshlrev_b32_e32 v133, 16, v187
	v_lshlrev_b32_e32 v228, 16, v183
	v_and_b32_e32 v187, 0xffff0000, v187
	v_and_b32_e32 v183, 0xffff0000, v183
	v_lshlrev_b32_e32 v134, 16, v188
	v_lshlrev_b32_e32 v229, 16, v184
	v_and_b32_e32 v188, 0xffff0000, v188
	v_and_b32_e32 v184, 0xffff0000, v184
	v_lshlrev_b32_e32 v135, 16, v189
	v_lshlrev_b32_e32 v230, 16, v185
	v_and_b32_e32 v189, 0xffff0000, v189
	v_and_b32_e32 v185, 0xffff0000, v185
	v_fmac_f32_e32 v132, v24, v227
	v_fmac_f32_e32 v186, v25, v182
	v_fmac_f32_e32 v133, v26, v228
	v_fmac_f32_e32 v187, v27, v183
	v_fmac_f32_e32 v134, v20, v229
	v_fmac_f32_e32 v188, v21, v184
	v_fmac_f32_e32 v135, v22, v230
	v_fmac_f32_e32 v189, v23, v185
	v_cvt_pk_bf16_f32 v182, v132, v186
	v_cvt_pk_bf16_f32 v183, v133, v187
	v_cvt_pk_bf16_f32 v184, v134, v188
	v_cvt_pk_bf16_f32 v185, v135, v189
	s_mov_b64 s[10:11], 0x50000
	v_lshl_add_u64 v[242:243], v[164:165], 0, s[10:11]
	global_store_dwordx4 v[242:243], v[182:185], off offset:256
	s_waitcnt vmcnt(7)
	v_lshlrev_b32_e32 v132, 16, v194
	v_lshlrev_b32_e32 v227, 16, v190
	v_and_b32_e32 v194, 0xffff0000, v194
	v_and_b32_e32 v190, 0xffff0000, v190
	v_lshlrev_b32_e32 v133, 16, v195
	v_lshlrev_b32_e32 v228, 16, v191
	v_and_b32_e32 v195, 0xffff0000, v195
	v_and_b32_e32 v191, 0xffff0000, v191
	v_lshlrev_b32_e32 v134, 16, v196
	v_lshlrev_b32_e32 v229, 16, v192
	v_and_b32_e32 v196, 0xffff0000, v196
	v_and_b32_e32 v192, 0xffff0000, v192
	v_lshlrev_b32_e32 v135, 16, v197
	v_lshlrev_b32_e32 v230, 16, v193
	v_and_b32_e32 v197, 0xffff0000, v197
	v_and_b32_e32 v193, 0xffff0000, v193
	v_fmac_f32_e32 v132, v16, v227
	v_fmac_f32_e32 v194, v17, v190
	v_fmac_f32_e32 v133, v18, v228
	v_fmac_f32_e32 v195, v19, v191
	v_fmac_f32_e32 v134, v12, v229
	v_fmac_f32_e32 v196, v13, v192
	v_fmac_f32_e32 v135, v14, v230
	v_fmac_f32_e32 v197, v15, v193
	v_cvt_pk_bf16_f32 v190, v132, v194
	v_cvt_pk_bf16_f32 v191, v133, v195
	v_cvt_pk_bf16_f32 v192, v134, v196
	v_cvt_pk_bf16_f32 v193, v135, v197
	s_mov_b64 s[10:11], 0x58000
	v_lshl_add_u64 v[242:243], v[164:165], 0, s[10:11]
	global_store_dwordx4 v[242:243], v[190:193], off
	s_waitcnt vmcnt(5)
	v_lshlrev_b32_e32 v132, 16, v206
	v_lshlrev_b32_e32 v227, 16, v202
	v_and_b32_e32 v206, 0xffff0000, v206
	v_and_b32_e32 v202, 0xffff0000, v202
	v_lshlrev_b32_e32 v133, 16, v207
	v_lshlrev_b32_e32 v228, 16, v203
	v_and_b32_e32 v207, 0xffff0000, v207
	v_and_b32_e32 v203, 0xffff0000, v203
	v_lshlrev_b32_e32 v134, 16, v208
	v_lshlrev_b32_e32 v229, 16, v204
	v_and_b32_e32 v208, 0xffff0000, v208
	v_and_b32_e32 v204, 0xffff0000, v204
	v_lshlrev_b32_e32 v135, 16, v209
	v_lshlrev_b32_e32 v230, 16, v205
	v_and_b32_e32 v209, 0xffff0000, v209
	v_and_b32_e32 v205, 0xffff0000, v205
	v_fmac_f32_e32 v132, v8, v227
	v_fmac_f32_e32 v206, v9, v202
	v_fmac_f32_e32 v133, v10, v228
	v_fmac_f32_e32 v207, v11, v203
	v_fmac_f32_e32 v134, v4, v229
	v_fmac_f32_e32 v208, v5, v204
	v_fmac_f32_e32 v135, v6, v230
	v_fmac_f32_e32 v209, v7, v205
	v_cvt_pk_bf16_f32 v202, v132, v206
	v_cvt_pk_bf16_f32 v203, v133, v207
	v_cvt_pk_bf16_f32 v204, v134, v208
	v_cvt_pk_bf16_f32 v205, v135, v209
	s_mov_b64 s[10:11], 0x58000
	v_lshl_add_u64 v[242:243], v[164:165], 0, s[10:11]
	global_store_dwordx4 v[242:243], v[202:205], off offset:256
	s_cbranch_execnz .LBB0_1006
; __device__ __forceinline__ float bflo(unsigned w) { return __uint_as_float(w << 16); }
;     __device__ __forceinline__ void op8(const size_t o, const f32x4 a0, const f32x4 a1) const {
;         const float a[8] = {a0[0], a0[1], a0[2], a0[3], a1[0], a1[1], a1[2], a1[3]};
;         u32x4 g = (u32x4){0u, 0u, 0u, 0u}, x = (u32x4){0u, 0u, 0u, 0u}, t = (u32x4){0u, 0u, 0u, 0u};
;         if (MODE == 0 || MODE == 1) g = *(const u32x4*)(G + o);
;         if (MODE == 1 || MODE == 4) t = *(const u32x4*)((const bf16*)T1 + o);
;         if (MODE == 2 || MODE == 4) x = *(const u32x4*)(X + o);
;         const unsigned gw[4] = {g.x, g.y, g.z, g.w}, xw[4] = {x.x, x.y, x.z, x.w}, tw[4] = {t.x, t.y, t.z, t.w};
;         unsigned w[4];
; #pragma unroll
;         for (int q = 0; q < 4; ++q) { float lo = 0.f, hi = 0.f;
;             if (MODE == 0) { lo = bflo(gw[q]) * a[2 * q]; hi = bfhi(gw[q]) * a[2 * q + 1]; }
;             if (MODE == 1) { lo = bflo(tw[q]) + bflo(gw[q]) * a[2 * q]; hi = bfhi(tw[q]) + bfhi(gw[q]) * a[2 * q + 1]; }
;             if (MODE == 2) { lo = bflo(xw[q]) * DN_ALPHA + a[2 * q]; hi = bfhi(xw[q]) * DN_ALPHA + a[2 * q + 1]; }
;             if (MODE == 3) { lo = a[2 * q]; hi = a[2 * q + 1]; }
;             if (MODE == 4) { lo = bflo(xw[q]) * DN_ALPHA + sigmoid_fast(a[2 * q]) * bflo(tw[q]); hi = bfhi(xw[q]) * DN_ALPHA + sigmoid_fast(a[2 * q + 1]) * bfhi(tw[q]); }
;             w[q] = pk2(lo, hi); }
;         const u32x4 ov = (u32x4){w[0], w[1], w[2], w[3]};
;         if (MODE == 0 || MODE == 3) *(u32x4*)((bf16*)T1 + o) = ov;
;         if (MODE == 1) *(u32x4*)(U + o) = ov;
;         if (MODE == 2) *(u32x4*)(X + o) = ov;
;         if (MODE == 4) *(u32x4*)(Xo + o) = ov;
;     }
;     __device__ __forceinline__ void operator()(const f32x4 (&acc)[2][2][4][2], const Unit& u, int wr, int wc, int fr, int fq) const {
;         const int col0 = u.pn * 256 + wc * 32 + 8 * fq;
; #pragma unroll
;         for (int ai = 0; ai < 2; ++ai)
; #pragma unroll
;             for (int m = 0; m < 4; ++m) {
;                 const size_t off = ((size_t)u.pm * 256 + ai * 128 + wr * 64 + m * 16 + fr) * 1024 + col0;
; #pragma unroll
;                 for (int bj = 0; bj < 2; ++bj) op8(off + bj * 128, acc[ai][bj][m][0], acc[ai][bj][m][1]);
;                 asm volatile("" ::: "memory");
;             }
;     }
.LBB0_1005:
	v_lshl_add_u64 v[132:133], s[4:5], 0, v[150:151]
	global_load_dwordx4 v[174:177], v[132:133], off
	global_load_dwordx4 v[178:181], v[132:133], off offset:256
	s_mov_b64 s[10:11], 0x8000
	v_lshl_add_u64 v[238:239], v[132:133], 0, s[10:11]
	global_load_dwordx4 v[182:185], v[238:239], off
	s_mov_b64 s[10:11], 0x8000
	v_lshl_add_u64 v[238:239], v[132:133], 0, s[10:11]
	global_load_dwordx4 v[186:189], v[238:239], off offset:256
	s_mov_b64 s[10:11], 0x10000
	v_lshl_add_u64 v[238:239], v[132:133], 0, s[10:11]
	global_load_dwordx4 v[190:193], v[238:239], off
	s_mov_b64 s[10:11], 0x10000
	v_lshl_add_u64 v[238:239], v[132:133], 0, s[10:11]
	global_load_dwordx4 v[194:197], v[238:239], off offset:256
	s_mov_b64 s[10:11], 0x18000
	v_lshl_add_u64 v[238:239], v[132:133], 0, s[10:11]
	global_load_dwordx4 v[202:205], v[238:239], off
	s_mov_b64 s[10:11], 0x18000
	v_lshl_add_u64 v[238:239], v[132:133], 0, s[10:11]
	global_load_dwordx4 v[206:209], v[238:239], off offset:256
	s_mov_b64 s[10:11], 0x40000
	v_lshl_add_u64 v[238:239], v[132:133], 0, s[10:11]
	global_load_dwordx4 v[210:213], v[238:239], off
	s_mov_b64 s[10:11], 0x40000
	v_lshl_add_u64 v[238:239], v[132:133], 0, s[10:11]
	global_load_dwordx4 v[214:217], v[238:239], off offset:256
	s_mov_b64 s[10:11], 0x48000
	v_lshl_add_u64 v[238:239], v[132:133], 0, s[10:11]
	global_load_dwordx4 v[218:221], v[238:239], off
	s_mov_b64 s[10:11], 0x48000
	v_lshl_add_u64 v[238:239], v[132:133], 0, s[10:11]
	global_load_dwordx4 v[222:225], v[238:239], off offset:256
	s_waitcnt vmcnt(11)
	v_lshlrev_b32_e32 v227, 16, v174
	v_and_b32_e32 v174, 0xffff0000, v174
	v_lshlrev_b32_e32 v228, 16, v175
	v_and_b32_e32 v175, 0xffff0000, v175
	v_lshlrev_b32_e32 v229, 16, v176
	v_and_b32_e32 v176, 0xffff0000, v176
	v_lshlrev_b32_e32 v230, 16, v177
	v_and_b32_e32 v177, 0xffff0000, v177
	v_mul_f32_e32 v227, v128, v227
	v_mul_f32_e32 v174, v129, v174
	v_mul_f32_e32 v228, v130, v228
	v_mul_f32_e32 v175, v131, v175
	v_mul_f32_e32 v229, v124, v229
	v_mul_f32_e32 v176, v125, v176
	v_mul_f32_e32 v230, v126, v230
	v_mul_f32_e32 v177, v127, v177
	v_cvt_pk_bf16_f32 v174, v227, v174
	v_cvt_pk_bf16_f32 v175, v228, v175
	v_cvt_pk_bf16_f32 v176, v229, v176
	v_cvt_pk_bf16_f32 v177, v230, v177
	global_store_dwordx4 v[148:149], v[174:177], off
	s_mov_b64 s[10:11], 0x50000
	v_lshl_add_u64 v[238:239], v[132:133], 0, s[10:11]
	global_load_dwordx4 v[174:177], v[238:239], off
	s_waitcnt vmcnt(12)
	v_lshlrev_b32_e32 v227, 16, v178
	v_and_b32_e32 v178, 0xffff0000, v178
	v_lshlrev_b32_e32 v228, 16, v179
	v_and_b32_e32 v179, 0xffff0000, v179
	v_lshlrev_b32_e32 v229, 16, v180
	v_and_b32_e32 v180, 0xffff0000, v180
	v_lshlrev_b32_e32 v230, 16, v181
	v_and_b32_e32 v181, 0xffff0000, v181
	v_mul_f32_e32 v227, v120, v227
	v_mul_f32_e32 v178, v121, v178
	v_mul_f32_e32 v228, v122, v228
	v_mul_f32_e32 v179, v123, v179
	v_mul_f32_e32 v229, v116, v229
	v_mul_f32_e32 v180, v117, v180
	v_mul_f32_e32 v230, v118, v230
	v_mul_f32_e32 v181, v119, v181
	v_cvt_pk_bf16_f32 v178, v227, v178
	v_cvt_pk_bf16_f32 v179, v228, v179
	v_cvt_pk_bf16_f32 v180, v229, v180
	v_cvt_pk_bf16_f32 v181, v230, v181
	global_store_dwordx4 v[148:149], v[178:181], off offset:256
	s_mov_b64 s[10:11], 0x50000
	v_lshl_add_u64 v[238:239], v[132:133], 0, s[10:11]
	global_load_dwordx4 v[178:181], v[238:239], off offset:256
	s_waitcnt vmcnt(13)
	v_lshlrev_b32_e32 v227, 16, v182
	v_and_b32_e32 v182, 0xffff0000, v182
	v_lshlrev_b32_e32 v228, 16, v183
	v_and_b32_e32 v183, 0xffff0000, v183
	v_lshlrev_b32_e32 v229, 16, v184
	v_and_b32_e32 v184, 0xffff0000, v184
	v_lshlrev_b32_e32 v230, 16, v185
	v_and_b32_e32 v185, 0xffff0000, v185
	v_mul_f32_e32 v227, v112, v227
	v_mul_f32_e32 v182, v113, v182
	v_mul_f32_e32 v228, v114, v228
	v_mul_f32_e32 v183, v115, v183
	v_mul_f32_e32 v229, v108, v229
	v_mul_f32_e32 v184, v109, v184
	v_mul_f32_e32 v230, v110, v230
	v_mul_f32_e32 v185, v111, v185
	v_cvt_pk_bf16_f32 v182, v227, v182
	v_cvt_pk_bf16_f32 v183, v228, v183
	v_cvt_pk_bf16_f32 v184, v229, v184
	v_cvt_pk_bf16_f32 v185, v230, v185
	s_mov_b64 s[10:11], 0x8000
	v_lshl_add_u64 v[240:241], v[148:149], 0, s[10:11]
	global_store_dwordx4 v[240:241], v[182:185], off
	s_mov_b64 s[10:11], 0x58000
	v_lshl_add_u64 v[238:239], v[132:133], 0, s[10:11]
	global_load_dwordx4 v[182:185], v[238:239], off
	s_waitcnt vmcnt(14)
	v_lshlrev_b32_e32 v227, 16, v186
	v_and_b32_e32 v186, 0xffff0000, v186
	v_lshlrev_b32_e32 v228, 16, v187
	v_and_b32_e32 v187, 0xffff0000, v187
	v_lshlrev_b32_e32 v229, 16, v188
	v_and_b32_e32 v188, 0xffff0000, v188
	v_lshlrev_b32_e32 v230, 16, v189
	v_and_b32_e32 v189, 0xffff0000, v189
	v_mul_f32_e32 v227, v104, v227
	v_mul_f32_e32 v186, v105, v186
	v_mul_f32_e32 v228, v106, v228
	v_mul_f32_e32 v187, v107, v187
	v_mul_f32_e32 v229, v100, v229
	v_mul_f32_e32 v188, v101, v188
	v_mul_f32_e32 v230, v102, v230
	v_mul_f32_e32 v189, v103, v189
	v_cvt_pk_bf16_f32 v186, v227, v186
	v_cvt_pk_bf16_f32 v187, v228, v187
	v_cvt_pk_bf16_f32 v188, v229, v188
	v_cvt_pk_bf16_f32 v189, v230, v189
	s_mov_b64 s[10:11], 0x8000
	v_lshl_add_u64 v[240:241], v[148:149], 0, s[10:11]
	global_store_dwordx4 v[240:241], v[186:189], off offset:256
	s_mov_b64 s[10:11], 0x58000
	v_lshl_add_u64 v[238:239], v[132:133], 0, s[10:11]
	global_load_dwordx4 v[186:189], v[238:239], off offset:256
	s_waitcnt vmcnt(15)
; __device__ __forceinline__ float bflo(unsigned w) { return __uint_as_float(w << 16); }
;     __device__ __forceinline__ void op8(const size_t o, const f32x4 a0, const f32x4 a1) const {
;         const float a[8] = {a0[0], a0[1], a0[2], a0[3], a1[0], a1[1], a1[2], a1[3]};
;         u32x4 g = (u32x4){0u, 0u, 0u, 0u}, x = (u32x4){0u, 0u, 0u, 0u}, t = (u32x4){0u, 0u, 0u, 0u};
;         if (MODE == 0 || MODE == 1) g = *(const u32x4*)(G + o);
;         if (MODE == 1 || MODE == 4) t = *(const u32x4*)((const bf16*)T1 + o);
;         if (MODE == 2 || MODE == 4) x = *(const u32x4*)(X + o);
;         const unsigned gw[4] = {g.x, g.y, g.z, g.w}, xw[4] = {x.x, x.y, x.z, x.w}, tw[4] = {t.x, t.y, t.z, t.w};
;         unsigned w[4];
; #pragma unroll
;         for (int q = 0; q < 4; ++q) { float lo = 0.f, hi = 0.f;
;             if (MODE == 0) { lo = bflo(gw[q]) * a[2 * q]; hi = bfhi(gw[q]) * a[2 * q + 1]; }
;             if (MODE == 1) { lo = bflo(tw[q]) + bflo(gw[q]) * a[2 * q]; hi = bfhi(tw[q]) + bfhi(gw[q]) * a[2 * q + 1]; }
;             if (MODE == 2) { lo = bflo(xw[q]) * DN_ALPHA + a[2 * q]; hi = bfhi(xw[q]) * DN_ALPHA + a[2 * q + 1]; }
;             if (MODE == 3) { lo = a[2 * q]; hi = a[2 * q + 1]; }
;             if (MODE == 4) { lo = bflo(xw[q]) * DN_ALPHA + sigmoid_fast(a[2 * q]) * bflo(tw[q]); hi = bfhi(xw[q]) * DN_ALPHA + sigmoid_fast(a[2 * q + 1]) * bfhi(tw[q]); }
;             w[q] = pk2(lo, hi); }
;         const u32x4 ov = (u32x4){w[0], w[1], w[2], w[3]};
;         if (MODE == 0 || MODE == 3) *(u32x4*)((bf16*)T1 + o) = ov;
;         if (MODE == 1) *(u32x4*)(U + o) = ov;
;         if (MODE == 2) *(u32x4*)(X + o) = ov;
;         if (MODE == 4) *(u32x4*)(Xo + o) = ov;
;     }
;     __device__ __forceinline__ void operator()(const f32x4 (&acc)[2][2][4][2], const Unit& u, int wr, int wc, int fr, int fq) const {
;         const int col0 = u.pn * 256 + wc * 32 + 8 * fq;
; #pragma unroll
;         for (int ai = 0; ai < 2; ++ai)
; #pragma unroll
;             for (int m = 0; m < 4; ++m) {
;                 const size_t off = ((size_t)u.pm * 256 + ai * 128 + wr * 64 + m * 16 + fr) * 1024 + col0;
; #pragma unroll
;                 for (int bj = 0; bj < 2; ++bj) op8(off + bj * 128, acc[ai][bj][m][0], acc[ai][bj][m][1]);
;                 asm volatile("" ::: "memory");
;             }
	v_lshlrev_b32_e32 v227, 16, v190
	v_and_b32_e32 v190, 0xffff0000, v190
	v_lshlrev_b32_e32 v228, 16, v191
	v_and_b32_e32 v191, 0xffff0000, v191
	v_lshlrev_b32_e32 v229, 16, v192
	v_and_b32_e32 v192, 0xffff0000, v192
	v_lshlrev_b32_e32 v230, 16, v193
	v_and_b32_e32 v193, 0xffff0000, v193
	v_mul_f32_e32 v227, v96, v227
	v_mul_f32_e32 v190, v97, v190
	v_mul_f32_e32 v228, v98, v228
	v_mul_f32_e32 v191, v99, v191
	v_mul_f32_e32 v229, v92, v229
	v_mul_f32_e32 v192, v93, v192
	v_mul_f32_e32 v230, v94, v230
	v_mul_f32_e32 v193, v95, v193
	v_cvt_pk_bf16_f32 v190, v227, v190
	v_cvt_pk_bf16_f32 v191, v228, v191
	v_cvt_pk_bf16_f32 v192, v229, v192
	v_cvt_pk_bf16_f32 v193, v230, v193
	s_mov_b64 s[10:11], 0x10000
	v_lshl_add_u64 v[240:241], v[148:149], 0, s[10:11]
	global_store_dwordx4 v[240:241], v[190:193], off
	s_waitcnt vmcnt(15)
	v_lshlrev_b32_e32 v227, 16, v194
	v_and_b32_e32 v194, 0xffff0000, v194
	v_lshlrev_b32_e32 v228, 16, v195
	v_and_b32_e32 v195, 0xffff0000, v195
	v_lshlrev_b32_e32 v229, 16, v196
	v_and_b32_e32 v196, 0xffff0000, v196
	v_lshlrev_b32_e32 v230, 16, v197
	v_and_b32_e32 v197, 0xffff0000, v197
	v_mul_f32_e32 v227, v88, v227
	v_mul_f32_e32 v194, v89, v194
	v_mul_f32_e32 v228, v90, v228
	v_mul_f32_e32 v195, v91, v195
	v_mul_f32_e32 v229, v84, v229
	v_mul_f32_e32 v196, v85, v196
	v_mul_f32_e32 v230, v86, v230
	v_mul_f32_e32 v197, v87, v197
	v_cvt_pk_bf16_f32 v194, v227, v194
	v_cvt_pk_bf16_f32 v195, v228, v195
	v_cvt_pk_bf16_f32 v196, v229, v196
	v_cvt_pk_bf16_f32 v197, v230, v197
	s_mov_b64 s[10:11], 0x10000
	v_lshl_add_u64 v[240:241], v[148:149], 0, s[10:11]
	global_store_dwordx4 v[240:241], v[194:197], off offset:256
	s_waitcnt vmcnt(15)
	v_lshlrev_b32_e32 v227, 16, v202
	v_and_b32_e32 v202, 0xffff0000, v202
	v_lshlrev_b32_e32 v228, 16, v203
	v_and_b32_e32 v203, 0xffff0000, v203
	v_lshlrev_b32_e32 v229, 16, v204
	v_and_b32_e32 v204, 0xffff0000, v204
	v_lshlrev_b32_e32 v230, 16, v205
	v_and_b32_e32 v205, 0xffff0000, v205
	v_mul_f32_e32 v227, v80, v227
	v_mul_f32_e32 v202, v81, v202
	v_mul_f32_e32 v228, v82, v228
	v_mul_f32_e32 v203, v83, v203
	v_mul_f32_e32 v229, v76, v229
	v_mul_f32_e32 v204, v77, v204
	v_mul_f32_e32 v230, v78, v230
	v_mul_f32_e32 v205, v79, v205
	v_cvt_pk_bf16_f32 v202, v227, v202
	v_cvt_pk_bf16_f32 v203, v228, v203
	v_cvt_pk_bf16_f32 v204, v229, v204
	v_cvt_pk_bf16_f32 v205, v230, v205
	s_mov_b64 s[10:11], 0x18000
	v_lshl_add_u64 v[240:241], v[148:149], 0, s[10:11]
	global_store_dwordx4 v[240:241], v[202:205], off
	s_waitcnt vmcnt(15)
	v_lshlrev_b32_e32 v227, 16, v206
	v_and_b32_e32 v206, 0xffff0000, v206
	v_lshlrev_b32_e32 v228, 16, v207
	v_and_b32_e32 v207, 0xffff0000, v207
	v_lshlrev_b32_e32 v229, 16, v208
	v_and_b32_e32 v208, 0xffff0000, v208
	v_lshlrev_b32_e32 v230, 16, v209
	v_and_b32_e32 v209, 0xffff0000, v209
	v_mul_f32_e32 v227, v72, v227
	v_mul_f32_e32 v206, v73, v206
	v_mul_f32_e32 v228, v74, v228
	v_mul_f32_e32 v207, v75, v207
	v_mul_f32_e32 v229, v68, v229
	v_mul_f32_e32 v208, v69, v208
	v_mul_f32_e32 v230, v70, v230
	v_mul_f32_e32 v209, v71, v209
	v_cvt_pk_bf16_f32 v206, v227, v206
	v_cvt_pk_bf16_f32 v207, v228, v207
	v_cvt_pk_bf16_f32 v208, v229, v208
	v_cvt_pk_bf16_f32 v209, v230, v209
	s_mov_b64 s[10:11], 0x18000
	v_lshl_add_u64 v[240:241], v[148:149], 0, s[10:11]
	global_store_dwordx4 v[240:241], v[206:209], off offset:256
	s_waitcnt vmcnt(15)
	v_lshlrev_b32_e32 v227, 16, v210
	v_and_b32_e32 v210, 0xffff0000, v210
	v_lshlrev_b32_e32 v228, 16, v211
	v_and_b32_e32 v211, 0xffff0000, v211
	v_lshlrev_b32_e32 v229, 16, v212
	v_and_b32_e32 v212, 0xffff0000, v212
	v_lshlrev_b32_e32 v230, 16, v213
	v_and_b32_e32 v213, 0xffff0000, v213
	v_mul_f32_e32 v227, v64, v227
	v_mul_f32_e32 v210, v65, v210
	v_mul_f32_e32 v228, v66, v228
	v_mul_f32_e32 v211, v67, v211
	v_mul_f32_e32 v229, v60, v229
	v_mul_f32_e32 v212, v61, v212
	v_mul_f32_e32 v230, v62, v230
	v_mul_f32_e32 v213, v63, v213
	v_cvt_pk_bf16_f32 v210, v227, v210
	v_cvt_pk_bf16_f32 v211, v228, v211
	v_cvt_pk_bf16_f32 v212, v229, v212
	v_cvt_pk_bf16_f32 v213, v230, v213
	s_mov_b64 s[10:11], 0x40000
	v_lshl_add_u64 v[240:241], v[148:149], 0, s[10:11]
	global_store_dwordx4 v[240:241], v[210:213], off
	s_waitcnt vmcnt(15)
	v_lshlrev_b32_e32 v227, 16, v214
	v_and_b32_e32 v214, 0xffff0000, v214
	v_lshlrev_b32_e32 v228, 16, v215
	v_and_b32_e32 v215, 0xffff0000, v215
	v_lshlrev_b32_e32 v229, 16, v216
	v_and_b32_e32 v216, 0xffff0000, v216
	v_lshlrev_b32_e32 v230, 16, v217
	v_and_b32_e32 v217, 0xffff0000, v217
	v_mul_f32_e32 v227, v56, v227
	v_mul_f32_e32 v214, v57, v214
	v_mul_f32_e32 v228, v58, v228
	v_mul_f32_e32 v215, v59, v215
	v_mul_f32_e32 v229, v52, v229
	v_mul_f32_e32 v216, v53, v216
	v_mul_f32_e32 v230, v54, v230
	v_mul_f32_e32 v217, v55, v217
	v_cvt_pk_bf16_f32 v214, v227, v214
	v_cvt_pk_bf16_f32 v215, v228, v215
	v_cvt_pk_bf16_f32 v216, v229, v216
	v_cvt_pk_bf16_f32 v217, v230, v217
	s_mov_b64 s[10:11], 0x40000
	v_lshl_add_u64 v[240:241], v[148:149], 0, s[10:11]
	global_store_dwordx4 v[240:241], v[214:217], off offset:256
	s_waitcnt vmcnt(15)
; __device__ __forceinline__ float bflo(unsigned w) { return __uint_as_float(w << 16); }
;     __device__ __forceinline__ void op8(const size_t o, const f32x4 a0, const f32x4 a1) const {
;         const float a[8] = {a0[0], a0[1], a0[2], a0[3], a1[0], a1[1], a1[2], a1[3]};
;         u32x4 g = (u32x4){0u, 0u, 0u, 0u}, x = (u32x4){0u, 0u, 0u, 0u}, t = (u32x4){0u, 0u, 0u, 0u};
;         if (MODE == 0 || MODE == 1) g = *(const u32x4*)(G + o);
;         if (MODE == 1 || MODE == 4) t = *(const u32x4*)((const bf16*)T1 + o);
;         if (MODE == 2 || MODE == 4) x = *(const u32x4*)(X + o);
;         const unsigned gw[4] = {g.x, g.y, g.z, g.w}, xw[4] = {x.x, x.y, x.z, x.w}, tw[4] = {t.x, t.y, t.z, t.w};
;         unsigned w[4];
; #pragma unroll
;         for (int q = 0; q < 4; ++q) { float lo = 0.f, hi = 0.f;
;             if (MODE == 0) { lo = bflo(gw[q]) * a[2 * q]; hi = bfhi(gw[q]) * a[2 * q + 1]; }
;             if (MODE == 1) { lo = bflo(tw[q]) + bflo(gw[q]) * a[2 * q]; hi = bfhi(tw[q]) + bfhi(gw[q]) * a[2 * q + 1]; }
;             if (MODE == 2) { lo = bflo(xw[q]) * DN_ALPHA + a[2 * q]; hi = bfhi(xw[q]) * DN_ALPHA + a[2 * q + 1]; }
;             if (MODE == 3) { lo = a[2 * q]; hi = a[2 * q + 1]; }
;             if (MODE == 4) { lo = bflo(xw[q]) * DN_ALPHA + sigmoid_fast(a[2 * q]) * bflo(tw[q]); hi = bfhi(xw[q]) * DN_ALPHA + sigmoid_fast(a[2 * q + 1]) * bfhi(tw[q]); }
;             w[q] = pk2(lo, hi); }
;         const u32x4 ov = (u32x4){w[0], w[1], w[2], w[3]};
;         if (MODE == 0 || MODE == 3) *(u32x4*)((bf16*)T1 + o) = ov;
;         if (MODE == 1) *(u32x4*)(U + o) = ov;
;         if (MODE == 2) *(u32x4*)(X + o) = ov;
;         if (MODE == 4) *(u32x4*)(Xo + o) = ov;
;     }
;     __device__ __forceinline__ void operator()(const f32x4 (&acc)[2][2][4][2], const Unit& u, int wr, int wc, int fr, int fq) const {
;         const int col0 = u.pn * 256 + wc * 32 + 8 * fq;
; #pragma unroll
;         for (int ai = 0; ai < 2; ++ai)
; #pragma unroll
;             for (int m = 0; m < 4; ++m) {
;                 const size_t off = ((size_t)u.pm * 256 + ai * 128 + wr * 64 + m * 16 + fr) * 1024 + col0;
; #pragma unroll
;                 for (int bj = 0; bj < 2; ++bj) op8(off + bj * 128, acc[ai][bj][m][0], acc[ai][bj][m][1]);
;                 asm volatile("" ::: "memory");
;             }
	v_lshlrev_b32_e32 v227, 16, v218
	v_and_b32_e32 v218, 0xffff0000, v218
	v_lshlrev_b32_e32 v228, 16, v219
	v_and_b32_e32 v219, 0xffff0000, v219
	v_lshlrev_b32_e32 v229, 16, v220
	v_and_b32_e32 v220, 0xffff0000, v220
	v_lshlrev_b32_e32 v230, 16, v221
	v_and_b32_e32 v221, 0xffff0000, v221
	v_mul_f32_e32 v227, v48, v227
	v_mul_f32_e32 v218, v49, v218
	v_mul_f32_e32 v228, v50, v228
	v_mul_f32_e32 v219, v51, v219
	v_mul_f32_e32 v229, v44, v229
	v_mul_f32_e32 v220, v45, v220
	v_mul_f32_e32 v230, v46, v230
	v_mul_f32_e32 v221, v47, v221
	v_cvt_pk_bf16_f32 v218, v227, v218
	v_cvt_pk_bf16_f32 v219, v228, v219
	v_cvt_pk_bf16_f32 v220, v229, v220
	v_cvt_pk_bf16_f32 v221, v230, v221
	s_mov_b64 s[10:11], 0x48000
	v_lshl_add_u64 v[240:241], v[148:149], 0, s[10:11]
	global_store_dwordx4 v[240:241], v[218:221], off
	s_waitcnt vmcnt(15)
	v_lshlrev_b32_e32 v227, 16, v222
	v_and_b32_e32 v222, 0xffff0000, v222
	v_lshlrev_b32_e32 v228, 16, v223
	v_and_b32_e32 v223, 0xffff0000, v223
	v_lshlrev_b32_e32 v229, 16, v224
	v_and_b32_e32 v224, 0xffff0000, v224
	v_lshlrev_b32_e32 v230, 16, v225
	v_and_b32_e32 v225, 0xffff0000, v225
	v_mul_f32_e32 v227, v40, v227
	v_mul_f32_e32 v222, v41, v222
	v_mul_f32_e32 v228, v42, v228
	v_mul_f32_e32 v223, v43, v223
	v_mul_f32_e32 v229, v36, v229
	v_mul_f32_e32 v224, v37, v224
	v_mul_f32_e32 v230, v38, v230
	v_mul_f32_e32 v225, v39, v225
	v_cvt_pk_bf16_f32 v222, v227, v222
	v_cvt_pk_bf16_f32 v223, v228, v223
	v_cvt_pk_bf16_f32 v224, v229, v224
	v_cvt_pk_bf16_f32 v225, v230, v225
	s_mov_b64 s[10:11], 0x48000
	v_lshl_add_u64 v[240:241], v[148:149], 0, s[10:11]
	global_store_dwordx4 v[240:241], v[222:225], off offset:256
	s_waitcnt vmcnt(14)
	v_lshlrev_b32_e32 v227, 16, v174
	v_and_b32_e32 v174, 0xffff0000, v174
	v_lshlrev_b32_e32 v228, 16, v175
	v_and_b32_e32 v175, 0xffff0000, v175
	v_lshlrev_b32_e32 v229, 16, v176
	v_and_b32_e32 v176, 0xffff0000, v176
	v_lshlrev_b32_e32 v230, 16, v177
	v_and_b32_e32 v177, 0xffff0000, v177
	v_mul_f32_e32 v227, v32, v227
	v_mul_f32_e32 v174, v33, v174
	v_mul_f32_e32 v228, v34, v228
	v_mul_f32_e32 v175, v35, v175
	v_mul_f32_e32 v229, v28, v229
	v_mul_f32_e32 v176, v29, v176
	v_mul_f32_e32 v230, v30, v230
	v_mul_f32_e32 v177, v31, v177
	v_cvt_pk_bf16_f32 v174, v227, v174
	v_cvt_pk_bf16_f32 v175, v228, v175
	v_cvt_pk_bf16_f32 v176, v229, v176
	v_cvt_pk_bf16_f32 v177, v230, v177
	s_mov_b64 s[10:11], 0x50000
	v_lshl_add_u64 v[240:241], v[148:149], 0, s[10:11]
	global_store_dwordx4 v[240:241], v[174:177], off
	s_waitcnt vmcnt(13)
	v_lshlrev_b32_e32 v227, 16, v178
	v_and_b32_e32 v178, 0xffff0000, v178
	v_lshlrev_b32_e32 v228, 16, v179
	v_and_b32_e32 v179, 0xffff0000, v179
	v_lshlrev_b32_e32 v229, 16, v180
	v_and_b32_e32 v180, 0xffff0000, v180
	v_lshlrev_b32_e32 v230, 16, v181
	v_and_b32_e32 v181, 0xffff0000, v181
	v_mul_f32_e32 v227, v24, v227
	v_mul_f32_e32 v178, v25, v178
	v_mul_f32_e32 v228, v26, v228
	v_mul_f32_e32 v179, v27, v179
	v_mul_f32_e32 v229, v20, v229
	v_mul_f32_e32 v180, v21, v180
	v_mul_f32_e32 v230, v22, v230
	v_mul_f32_e32 v181, v23, v181
	v_cvt_pk_bf16_f32 v178, v227, v178
	v_cvt_pk_bf16_f32 v179, v228, v179
	v_cvt_pk_bf16_f32 v180, v229, v180
	v_cvt_pk_bf16_f32 v181, v230, v181
	s_mov_b64 s[10:11], 0x50000
	v_lshl_add_u64 v[240:241], v[148:149], 0, s[10:11]
	global_store_dwordx4 v[240:241], v[178:181], off offset:256
	s_waitcnt vmcnt(12)
	v_lshlrev_b32_e32 v227, 16, v182
	v_and_b32_e32 v182, 0xffff0000, v182
	v_lshlrev_b32_e32 v228, 16, v183
	v_and_b32_e32 v183, 0xffff0000, v183
	v_lshlrev_b32_e32 v229, 16, v184
	v_and_b32_e32 v184, 0xffff0000, v184
	v_lshlrev_b32_e32 v230, 16, v185
	v_and_b32_e32 v185, 0xffff0000, v185
	v_mul_f32_e32 v227, v16, v227
	v_mul_f32_e32 v182, v17, v182
	v_mul_f32_e32 v228, v18, v228
	v_mul_f32_e32 v183, v19, v183
	v_mul_f32_e32 v229, v12, v229
	v_mul_f32_e32 v184, v13, v184
	v_mul_f32_e32 v230, v14, v230
	v_mul_f32_e32 v185, v15, v185
	v_cvt_pk_bf16_f32 v182, v227, v182
	v_cvt_pk_bf16_f32 v183, v228, v183
	v_cvt_pk_bf16_f32 v184, v229, v184
	v_cvt_pk_bf16_f32 v185, v230, v185
	s_mov_b64 s[10:11], 0x58000
	v_lshl_add_u64 v[240:241], v[148:149], 0, s[10:11]
	global_store_dwordx4 v[240:241], v[182:185], off
	s_waitcnt vmcnt(11)
	v_lshlrev_b32_e32 v227, 16, v186
	v_and_b32_e32 v186, 0xffff0000, v186
	v_lshlrev_b32_e32 v228, 16, v187
	v_and_b32_e32 v187, 0xffff0000, v187
	v_lshlrev_b32_e32 v229, 16, v188
	v_and_b32_e32 v188, 0xffff0000, v188
	v_lshlrev_b32_e32 v230, 16, v189
	v_and_b32_e32 v189, 0xffff0000, v189
	v_mul_f32_e32 v227, v8, v227
	v_mul_f32_e32 v186, v9, v186
	v_mul_f32_e32 v228, v10, v228
	v_mul_f32_e32 v187, v11, v187
	v_mul_f32_e32 v229, v4, v229
	v_mul_f32_e32 v188, v5, v188
	v_mul_f32_e32 v230, v6, v230
	v_mul_f32_e32 v189, v7, v189
	v_cvt_pk_bf16_f32 v186, v227, v186
	v_cvt_pk_bf16_f32 v187, v228, v187
	v_cvt_pk_bf16_f32 v188, v229, v188
	v_cvt_pk_bf16_f32 v189, v230, v189
	s_mov_b64 s[10:11], 0x58000
	v_lshl_add_u64 v[240:241], v[148:149], 0, s[10:11]
	global_store_dwordx4 v[240:241], v[186:189], off offset:256
